# grid barrier 1 XCD-local too: H rows written by the reading class, transposed weights published by write-through stores plus per-workgroup completion words summed by an idle wave during the barrier
# baseline (speedup 1.0000x reference)
; #define LAS __attribute__((address_space(3)))
; __device__ __forceinline__ unsigned pk2(float lo, float hi) { f32x2 v = {lo, hi}; bf16x2_t b = __builtin_convertvector(v, bf16x2_t); return __builtin_bit_cast(unsigned, b); }
; __device__ __forceinline__ void transpose_item(const float* W, int K, int N, bf16* WT, const float* gain, LAS float* scr, int item, int nblk, int lane) {
;     ...
; #pragma unroll
;     for (int i = 0; i < 16; ++i) { LAS float* d = scr + (4 * i + kr) * 65 + nc; d[0] = v[i].x; d[1] = v[i].y; d[2] = v[i].z; d[3] = v[i].w; }
;     asm volatile("s_waitcnt lgkmcnt(0)" ::: "memory");
;     const int c = lane & 7;
; #pragma unroll
;     for (int j = 0; j < 8; ++j) { const int n = (lane >> 3) + 8 * j; const LAS float* sp = scr + (8 * c) * 65 + n;
;         u32x4 o; o.x = pk2(sp[0 * 65], sp[1 * 65]); o.y = pk2(sp[2 * 65], sp[3 * 65]); o.z = pk2(sp[4 * 65], sp[5 * 65]); o.w = pk2(sp[6 * 65], sp[7 * 65]);
;         *(u32x4*)(WT + (size_t)(n0 + n) * K + k0 + 8 * c) = o; }
;     asm volatile("s_waitcnt lgkmcnt(0)" ::: "memory");
; __device__ __forceinline__ void p0_prologue(const Args& a, LAS unsigned char* lds) {
;     ...
;         if (r < I_IN) { transpose_item(a.w_in, D_, INW, (bf16*)(ws + WS_WIN), nullptr, scr, r, NPROJ / 64, lane); continue; } r -= I_IN;
.LBB0_7:
	s_or_b64 exec, exec, s[14:15]
	s_waitcnt vmcnt(0)
	ds_write2_b32 v96, v8, v9 offset1:1
	ds_write2_b32 v96, v10, v11 offset0:2 offset1:3
	v_add_u32_e32 v8, 0x410, v96
	ds_write2_b32 v8, v4, v5 offset1:1
	v_add_u32_e32 v4, 0x418, v96
	ds_write2_b32 v4, v6, v7 offset1:1
	v_add_u32_e32 v4, 0x820, v96
	ds_write2_b32 v4, v16, v17 offset1:1
	v_add_u32_e32 v4, 0x828, v96
	ds_write2_b32 v4, v18, v19 offset1:1
	v_add_u32_e32 v4, 0xc30, v96
	ds_write2_b32 v4, v12, v13 offset1:1
	v_add_u32_e32 v4, 0xc38, v96
	ds_write2_b32 v4, v14, v15 offset1:1
	v_add_u32_e32 v4, 0x1040, v96
	ds_write2_b32 v4, v24, v25 offset1:1
	v_add_u32_e32 v4, 0x1048, v96
	ds_write2_b32 v4, v26, v27 offset1:1
	v_add_u32_e32 v4, 0x1450, v96
	ds_write2_b32 v4, v20, v21 offset1:1
	v_add_u32_e32 v4, 0x1458, v96
	ds_write2_b32 v4, v22, v23 offset1:1
	v_add_u32_e32 v4, 0x1860, v96
	ds_write2_b32 v4, v32, v33 offset1:1
	v_add_u32_e32 v4, 0x1868, v96
	ds_write2_b32 v4, v34, v35 offset1:1
	v_add_u32_e32 v4, 0x1c70, v96
	ds_write2_b32 v4, v28, v29 offset1:1
	v_add_u32_e32 v4, 0x1c78, v96
	ds_write2_b32 v4, v30, v31 offset1:1
	v_add_u32_e32 v4, 0x2080, v96
	ds_write2_b32 v4, v40, v41 offset1:1
	v_add_u32_e32 v4, 0x2088, v96
	ds_write2_b32 v4, v42, v43 offset1:1
	v_add_u32_e32 v4, 0x2490, v96
	ds_write2_b32 v4, v36, v37 offset1:1
	v_add_u32_e32 v4, 0x2498, v96
	ds_write2_b32 v4, v38, v39 offset1:1
	v_add_u32_e32 v4, 0x28a0, v96
	ds_write2_b32 v4, v48, v49 offset1:1
	v_add_u32_e32 v4, 0x28a8, v96
	ds_write2_b32 v4, v50, v51 offset1:1
	v_add_u32_e32 v4, 0x2cb0, v96
	ds_write2_b32 v4, v44, v45 offset1:1
	v_add_u32_e32 v4, 0x2cb8, v96
	ds_write2_b32 v4, v46, v47 offset1:1
	v_add_u32_e32 v4, 0x30c0, v96
	ds_write2_b32 v4, v56, v57 offset1:1
	v_add_u32_e32 v4, 0x30c8, v96
	ds_write2_b32 v4, v58, v59 offset1:1
	v_add_u32_e32 v4, 0x34d0, v96
	ds_write2_b32 v4, v52, v53 offset1:1
	v_add_u32_e32 v4, 0x34d8, v96
	ds_write2_b32 v4, v54, v55 offset1:1
	v_add_u32_e32 v4, 0x38e0, v96
	ds_write2_b32 v4, v64, v65 offset1:1
	v_add_u32_e32 v4, 0x38e8, v96
	ds_write2_b32 v4, v66, v67 offset1:1
	v_add_u32_e32 v4, 0x3cf0, v96
	ds_write2_b32 v4, v60, v61 offset1:1
	v_add_u32_e32 v4, 0x3cf8, v96
	ds_write2_b32 v4, v62, v63 offset1:1
	s_waitcnt lgkmcnt(0)
	v_add_u32_e32 v30, 0x400, v98
	ds_read2_b32 v[8:9], v98 offset0:65 offset1:73
	ds_read2_b32 v[10:11], v98 offset1:8
	ds_read2_b32 v[12:13], v98 offset0:130 offset1:138
	ds_read2_b32 v[14:15], v98 offset0:195 offset1:203
	ds_read2_b32 v[16:17], v30 offset0:4 offset1:12
	ds_read2_b32 v[18:19], v30 offset0:69 offset1:77
	ds_read2_b32 v[20:21], v30 offset0:134 offset1:142
	ds_read2_b32 v[22:23], v30 offset0:199 offset1:207
	v_sub_u32_e32 v3, 0, v3
	v_add3_u32 v26, v97, v106, v3
	v_ashrrev_i32_e32 v69, 31, v68
	v_ashrrev_i32_e32 v27, 31, v26
	v_lshl_add_u64 v[24:25], v[68:69], 1, v[78:79]
	v_lshlrev_b64 v[28:29], 11, v[26:27]
	s_waitcnt lgkmcnt(6)
	v_cvt_pk_bf16_f32 v4, v10, v8
	s_waitcnt lgkmcnt(4)
	v_cvt_pk_bf16_f32 v5, v12, v14
	s_waitcnt lgkmcnt(2)
	v_cvt_pk_bf16_f32 v6, v16, v18
	s_waitcnt lgkmcnt(0)
	v_cvt_pk_bf16_f32 v7, v20, v22
	v_lshl_add_u64 v[28:29], v[24:25], 0, v[28:29]
	v_add_u32_e32 v8, 8, v26
	global_store_dwordx4 v[28:29], v[4:7], off sc0 sc1
	s_nop 1
	v_cvt_pk_bf16_f32 v4, v11, v9
	v_ashrrev_i32_e32 v9, 31, v8
	v_cvt_pk_bf16_f32 v5, v13, v15
	v_cvt_pk_bf16_f32 v6, v17, v19
	v_cvt_pk_bf16_f32 v7, v21, v23
	v_lshlrev_b64 v[8:9], 11, v[8:9]
	ds_read2_b32 v[10:11], v98 offset0:81 offset1:89
	ds_read2_b32 v[12:13], v98 offset0:16 offset1:24
	ds_read2_b32 v[14:15], v98 offset0:146 offset1:154
	ds_read2_b32 v[16:17], v98 offset0:211 offset1:219
	ds_read2_b32 v[18:19], v30 offset0:20 offset1:28
	ds_read2_b32 v[20:21], v30 offset0:85 offset1:93
	ds_read2_b32 v[22:23], v30 offset0:150 offset1:158
	ds_read2_b32 v[28:29], v30 offset0:215 offset1:223
	v_lshl_add_u64 v[8:9], v[24:25], 0, v[8:9]
	global_store_dwordx4 v[8:9], v[4:7], off sc0 sc1
	v_add_u32_e32 v8, 16, v26
	v_ashrrev_i32_e32 v9, 31, v8
	v_lshlrev_b64 v[8:9], 11, v[8:9]
	s_waitcnt lgkmcnt(6)
	v_cvt_pk_bf16_f32 v4, v12, v10
	s_waitcnt lgkmcnt(4)
	v_cvt_pk_bf16_f32 v5, v14, v16
	s_waitcnt lgkmcnt(2)
	v_cvt_pk_bf16_f32 v6, v18, v20
	s_waitcnt lgkmcnt(0)
	v_cvt_pk_bf16_f32 v7, v22, v28
	v_lshl_add_u64 v[8:9], v[24:25], 0, v[8:9]
	global_store_dwordx4 v[8:9], v[4:7], off sc0 sc1
	v_add_u32_e32 v8, 24, v26
	v_ashrrev_i32_e32 v9, 31, v8
	v_cvt_pk_bf16_f32 v4, v13, v11
	v_cvt_pk_bf16_f32 v5, v15, v17
	v_cvt_pk_bf16_f32 v6, v19, v21
	v_cvt_pk_bf16_f32 v7, v23, v29
	v_lshlrev_b64 v[8:9], 11, v[8:9]
	ds_read2_b32 v[10:11], v98 offset0:32 offset1:40
	ds_read2_b32 v[12:13], v98 offset0:97 offset1:105
	ds_read2_b32 v[14:15], v98 offset0:162 offset1:170
	ds_read2_b32 v[16:17], v98 offset0:227 offset1:235
	ds_read2_b32 v[18:19], v30 offset0:36 offset1:44
	ds_read2_b32 v[20:21], v30 offset0:101 offset1:109
	ds_read2_b32 v[22:23], v30 offset0:166 offset1:174
	ds_read2_b32 v[28:29], v30 offset0:231 offset1:239
	v_lshl_add_u64 v[8:9], v[24:25], 0, v[8:9]
	global_store_dwordx4 v[8:9], v[4:7], off sc0 sc1
	v_add_u32_e32 v8, 32, v26
	v_ashrrev_i32_e32 v9, 31, v8
	v_lshlrev_b64 v[8:9], 11, v[8:9]
	s_waitcnt lgkmcnt(6)
	v_cvt_pk_bf16_f32 v4, v10, v12
	s_waitcnt lgkmcnt(4)
	v_cvt_pk_bf16_f32 v5, v14, v16
	s_waitcnt lgkmcnt(2)
	v_cvt_pk_bf16_f32 v6, v18, v20
	s_waitcnt lgkmcnt(0)
	v_cvt_pk_bf16_f32 v7, v22, v28
	v_lshl_add_u64 v[8:9], v[24:25], 0, v[8:9]
	global_store_dwordx4 v[8:9], v[4:7], off sc0 sc1
	v_add_u32_e32 v8, 40, v26
	v_ashrrev_i32_e32 v9, 31, v8
	v_cvt_pk_bf16_f32 v4, v11, v13
	v_cvt_pk_bf16_f32 v5, v15, v17
	v_cvt_pk_bf16_f32 v6, v19, v21
	v_cvt_pk_bf16_f32 v7, v23, v29
	v_lshlrev_b64 v[8:9], 11, v[8:9]
	ds_read2_b32 v[10:11], v98 offset0:48 offset1:56
	ds_read2_b32 v[12:13], v98 offset0:113 offset1:121
	ds_read2_b32 v[14:15], v98 offset0:178 offset1:186
	ds_read2_b32 v[16:17], v98 offset0:243 offset1:251
	ds_read2_b32 v[18:19], v30 offset0:52 offset1:60
	ds_read2_b32 v[20:21], v30 offset0:117 offset1:125
	ds_read2_b32 v[22:23], v30 offset0:182 offset1:190
	ds_read2_b32 v[28:29], v30 offset0:247 offset1:255
	v_lshl_add_u64 v[8:9], v[24:25], 0, v[8:9]
	global_store_dwordx4 v[8:9], v[4:7], off sc0 sc1
	v_add_u32_e32 v8, 48, v26
	v_ashrrev_i32_e32 v9, 31, v8
	v_lshlrev_b64 v[8:9], 11, v[8:9]
	s_waitcnt lgkmcnt(6)
	v_cvt_pk_bf16_f32 v4, v10, v12
	s_waitcnt lgkmcnt(4)
	v_cvt_pk_bf16_f32 v5, v14, v16
	s_waitcnt lgkmcnt(2)
	v_cvt_pk_bf16_f32 v6, v18, v20
	s_waitcnt lgkmcnt(0)
	v_cvt_pk_bf16_f32 v7, v22, v28
	v_lshl_add_u64 v[8:9], v[24:25], 0, v[8:9]
	global_store_dwordx4 v[8:9], v[4:7], off sc0 sc1
	v_add_u32_e32 v8, 56, v26
	v_ashrrev_i32_e32 v9, 31, v8
	v_lshlrev_b64 v[8:9], 11, v[8:9]
	v_cvt_pk_bf16_f32 v4, v11, v13
	v_cvt_pk_bf16_f32 v5, v15, v17
	v_cvt_pk_bf16_f32 v6, v19, v21
	v_cvt_pk_bf16_f32 v7, v23, v29
	v_lshl_add_u64 v[8:9], v[24:25], 0, v[8:9]
	global_store_dwordx4 v[8:9], v[4:7], off sc0 sc1
	s_waitcnt lgkmcnt(0)

; __device__ __forceinline__ void rms_row_to_bf16(const float* xrow, const float* g, bf16* orow, int lane) {
;     const f32x4* xr = (const f32x4*)xrow + lane; const f32x4* gr = (const f32x4*)g + lane;
;     f32x4 v[4]; float s = 0.f;
; __device__ __forceinline__ void p0_prologue(const Args& a, LAS unsigned char* lds) {
;     ...
;     bf16* H = (bf16*)(ws + WS_HB);
;     for (int m = gw; m < T_; m += NGW) rms_row_to_bf16(a.x + (size_t)m * D_, a.ln_mix_g, H + (size_t)m * D_, lane);
.LBB0_92:
	v_readfirstlane_b32 s98, v70
	s_nop 3
	s_cmp_eq_u32 s94, 0x100
	s_cbranch_scc0 .Lrms_nb
	s_and_b32 s99, s2, 7
	s_lshl_b32 s99, s99, 11
	s_lshr_b32 s100, s2, 3
	s_lshl_b32 s100, s100, 3
	s_add_i32 s99, s99, s100
	s_lshl_b32 s100, s2, 3
	s_sub_i32 s100, s99, s100
	s_ashr_i32 s101, s100, 31
	s_lshl_b64 s[100:101], s[100:101], 11
	v_lshl_add_u64 v[4:5], s[100:101], 0, v[4:5]
	s_lshl_b64 s[100:101], s[100:101], 1
	v_lshl_add_u64 v[6:7], s[100:101], 0, v[6:7]
	s_mov_b32 s12, 0x80000
	s_mov_b32 s13, 0
	s_mov_b32 s14, 0x100000
	s_mov_b32 s15, 0
.Lrms_nb:
	s_mov_b32 s100, 0
	global_load_dwordx4 v[32:35], v[2:3], off
	global_load_dwordx4 v[72:75], v[2:3], off offset:1024
	global_load_dwordx4 v[76:79], v[2:3], off offset:2048
	global_load_dwordx4 v[80:83], v[2:3], off offset:3072
	global_load_dwordx4 v[16:19], v[6:7], off offset:-3072 nt
	global_load_dwordx4 v[20:23], v[6:7], off offset:-2048 nt
	global_load_dwordx4 v[24:27], v[6:7], off offset:-1024 nt
	global_load_dwordx4 v[28:31], v[6:7], off nt

; __device__ __forceinline__ void rms_row_to_bf16(const float* xrow, const float* g, bf16* orow, int lane) {
;     const f32x4* xr = (const f32x4*)xrow + lane; const f32x4* gr = (const f32x4*)g + lane;
;     f32x4 v[4]; float s = 0.f;
; #pragma unroll
;     for (int j = 0; j < 4; ++j) { v[j] = xr[64 * j]; s += (v[j].x * v[j].x + v[j].y * v[j].y) + (v[j].z * v[j].z + v[j].w * v[j].w); }
;     const float rstd = 1.f / sqrtf(wave_sum(s) * (1.f / D_) + EPS);
.Lrms_go_a:
	s_cmp_lg_u32 s100, 0
	s_cbranch_scc1 .Lrms_noarr
	s_cmp_lt_u32 s98, 0x350
	s_cbranch_scc0 .Lrms_noarr
	s_and_b32 s99, s2, 31
	s_lshl_b32 s99, s99, 8
	s_lshr_b32 s100, s2, 5
	s_lshl_b32 s100, s100, 2
	s_add_i32 s99, s99, s100
	s_add_u32 s99, s99, 0xff40480
	s_add_u32 s100, s92, s99
	s_addc_u32 s101, s93, 0
	s_mov_b64 exec, 1
	v_mov_b32_e32 v228, 0
	v_mov_b32_e32 v229, 1
	global_atomic_add v228, v229, s[100:101]
	s_mov_b64 exec, -1
	s_mov_b32 s100, 0

; __device__ __forceinline__ unsigned xb_ld(unsigned* p)              { return __hip_atomic_load(p, __ATOMIC_RELAXED, __HIP_MEMORY_SCOPE_AGENT); }
; __device__ __forceinline__ unsigned xb_add(unsigned* p, unsigned v) { return __hip_atomic_fetch_add(p, v, __ATOMIC_RELAXED, __HIP_MEMORY_SCOPE_AGENT); }
; #define XB_SPIN(cond, bar) do { unsigned _sp = 0; while (cond) { __builtin_amdgcn_s_sleep(1); \
;     if ((++_sp & 255u) == 0u) { if (xb_ld(&(bar)[XB_TMO])) break; if (_sp > XB_SPIN_CAP) { atomicAdd(&(bar)[XB_TMO], 1u); break; } } } } while (0)
; __device__ __forceinline__ void xcd_barrier(const XcdBarrier& b) {
;     asm volatile("s_waitcnt vmcnt(0)" ::: "memory");
;     __syncthreads();
;     if (threadIdx.x == 0) {
;         unsigned* bar = b.bar;
;         __builtin_amdgcn_s_waitcnt(0);
;         unsigned nloc = b.st[0], nx = b.st[1];
;         if (nloc == 0u) { xcd_barrier_complete(bar, b.x, nloc, nx); b.st[0] = nloc; b.st[1] = nx; }
;         const unsigned old = xb_add(&bar[XB_XSUB(b.x)], 1u);
;         const unsigned gen = old / nloc;
;         if (old + 1u == (gen + 1u) * nloc) {
;             __builtin_amdgcn_fence(__ATOMIC_RELEASE, "agent");
;             asm volatile("s_waitcnt vmcnt(0)" ::: "memory");
;             const unsigned og = xb_add(&bar[XB_TOP], 1u);
;             const unsigned tg = og / nx;
;             if (og + 1u == (tg + 1u) * nx) xb_add(&bar[XB_TOPGEN], 1u);
;             else XB_SPIN(xb_ld(&bar[XB_TOPGEN]) == tg, bar);
; __global__ void __launch_bounds__(NTHREADS, 2) fwd_megakernel(Args a) {
;     ...
;         float mq = 0.f, mk = 0.f;
;         for (int i = 0; i < 96; ++i) { mq = fmaxf(mq, fabsf(a.q_norm_g[i])); mk = fmaxf(mk, fabsf(a.k_norm_g[i])); }
;         const float mb = fminf(96.f * mq * mk * 0.10206207261596577f * LOG2E, 80.f);
.Lcen_done:
	v_bcnt_u32_b32 v4, v2, 0
	v_bcnt_u32_b32 v4, v3, v4
	v_cmp_eq_u32_e32 vcc, 1, v4
	s_nop 1
	s_mov_b64 s[100:101], vcc
	v_cmp_eq_u32_e32 vcc, 32, v1
	s_nop 1
	s_and_b64 s[100:101], s[100:101], vcc
	v_or_b32_e32 v4, v2, v3
	v_cmp_eq_u32_e32 vcc, 0, v4
	s_nop 1
	s_or_b64 s[100:101], s[100:101], vcc
	s_andn2_b64 s[100:101], exec, s[100:101]
	s_cmp_eq_u64 s[100:101], 0
	s_cselect_b32 s100, 2, 1
	v_mov_b32_e32 v0, 0x23030
	v_mov_b32_e32 v1, s100
	ds_write_b32 v0, v1
	s_waitcnt lgkmcnt(0)
	v_mbcnt_lo_u32_b32 v0, -1, 0
	v_mbcnt_hi_u32_b32 v0, -1, v0
	v_cmp_gt_u32_e32 vcc, 24, v0
	v_lshlrev_b32_e32 v1, 4, v0
	v_mov_b32_e32 v2, 0
	v_mov_b32_e32 v3, 0
	v_mov_b32_e32 v4, 0
	v_mov_b32_e32 v5, 0
	v_mov_b32_e32 v6, 0
	v_mov_b32_e32 v7, 0
	v_mov_b32_e32 v8, 0
	v_mov_b32_e32 v9, 0
	s_and_saveexec_b64 s[100:101], vcc
	global_load_dwordx4 v[2:5], v1, s[72:73]
	global_load_dwordx4 v[6:9], v1, s[74:75]
	s_or_b64 exec, exec, s[100:101]
	s_waitcnt vmcnt(0)
	v_max3_f32 v2, |v2|, |v3|, |v4|
	v_max_f32_e64 v2, v2, |v5|
	v_max3_f32 v6, |v6|, |v7|, |v8|
	v_max_f32_e64 v6, v6, |v9|
	s_nop 1
	v_max_f32_dpp v10, v2, v2 row_ror:8 row_mask:0xf bank_mask:0xf
	s_nop 1
	v_max_f32_dpp v11, v10, v10 row_ror:4 row_mask:0xf bank_mask:0xf
	s_nop 1
	v_max_f32_dpp v12, v11, v11 row_ror:2 row_mask:0xf bank_mask:0xf
	s_nop 1
	v_max_f32_dpp v2, v12, v12 row_ror:1 row_mask:0xf bank_mask:0xf
	s_nop 1
	v_max_f32_dpp v13, v6, v6 row_ror:8 row_mask:0xf bank_mask:0xf
	s_nop 1
	v_max_f32_dpp v14, v13, v13 row_ror:4 row_mask:0xf bank_mask:0xf
	s_nop 1
	v_max_f32_dpp v15, v14, v14 row_ror:2 row_mask:0xf bank_mask:0xf
	s_nop 1
	v_max_f32_dpp v6, v15, v15 row_ror:1 row_mask:0xf bank_mask:0xf
	s_nop 1
	v_readlane_b32 s98, v2, 0
	v_readlane_b32 s99, v2, 16
	v_readlane_b32 s100, v6, 0
	v_readlane_b32 s101, v6, 16
	v_mov_b32_e32 v2, s98
	v_max_f32_e32 v2, s99, v2
	v_mov_b32_e32 v3, s100
	v_max_f32_e32 v3, s101, v3
	v_mov_b32_e32 v0, 0x23034
	ds_write2_b32 v0, v2, v3 offset1:1
	s_waitcnt lgkmcnt(0)
	s_branch .Lbinv_1
.Lw2_1:
	s_cmp_lg_u32 s100, 2
	s_cbranch_scc1 .Lbinv_1
	s_add_u32 s100, s92, 0xff40480
	s_addc_u32 s101, s93, 0
	s_lshl_b32 s99, s94, 3
	s_min_u32 s99, s99, 0x350
	v_mbcnt_lo_u32_b32 v0, -1, 0
	v_mbcnt_hi_u32_b32 v0, -1, v0
	v_and_b32_e32 v2, 31, v0
	v_lshlrev_b32_e32 v2, 8, v2
	v_mov_b32_e32 v11, 0
	s_nop 1
.Lw2_p:
	global_load_dwordx4 v[4:7], v2, s[100:101] sc1
	s_waitcnt vmcnt(0)
	v_add3_u32 v3, v4, v5, v6
	v_add_u32_e32 v3, v3, v7
	v_cmp_gt_u32_e32 vcc, 32, v0
	s_nop 1
	v_cndmask_b32_e32 v3, 0, v3, vcc
	s_nop 1
	v_add_u32_dpp v8, v3, v3 row_ror:8 row_mask:0xf bank_mask:0xf
	s_nop 1
	v_add_u32_dpp v9, v8, v8 row_ror:4 row_mask:0xf bank_mask:0xf
	s_nop 1
	v_add_u32_dpp v10, v9, v9 row_ror:2 row_mask:0xf bank_mask:0xf
	s_nop 1
	v_add_u32_dpp v3, v10, v10 row_ror:1 row_mask:0xf bank_mask:0xf
	s_nop 1
	v_readlane_b32 s98, v3, 16
	s_nop 3
	v_add_u32_e32 v9, s98, v3
	s_nop 1
	v_readfirstlane_b32 s98, v9
	s_nop 3
	s_cmp_ge_u32 s98, s99
	s_cbranch_scc1 .Lbinv_1
	s_sleep 2
	v_add_u32_e32 v11, 1, v11
	s_nop 1
	v_readfirstlane_b32 s98, v11
	s_nop 3
	s_cmp_lt_u32 s98, 0x100000
	s_cbranch_scc1 .Lw2_p

; __device__ __forceinline__ unsigned xb_ld(unsigned* p)              { return __hip_atomic_load(p, __ATOMIC_RELAXED, __HIP_MEMORY_SCOPE_AGENT); }
; __device__ __forceinline__ unsigned xb_add(unsigned* p, unsigned v) { return __hip_atomic_fetch_add(p, v, __ATOMIC_RELAXED, __HIP_MEMORY_SCOPE_AGENT); }
; #define XB_SPIN(cond, bar) do { unsigned _sp = 0; while (cond) { __builtin_amdgcn_s_sleep(1); \
;     if ((++_sp & 255u) == 0u) { if (xb_ld(&(bar)[XB_TMO])) break; if (_sp > XB_SPIN_CAP) { atomicAdd(&(bar)[XB_TMO], 1u); break; } } } } while (0)
; __device__ __forceinline__ void xcd_barrier(const XcdBarrier& b) {
;     asm volatile("s_waitcnt vmcnt(0)" ::: "memory");
;     __syncthreads();
;     if (threadIdx.x == 0) {
;         unsigned* bar = b.bar;
;         __builtin_amdgcn_s_waitcnt(0);
;         unsigned nloc = b.st[0], nx = b.st[1];
;         if (nloc == 0u) { xcd_barrier_complete(bar, b.x, nloc, nx); b.st[0] = nloc; b.st[1] = nx; }
;         const unsigned old = xb_add(&bar[XB_XSUB(b.x)], 1u);
;         const unsigned gen = old / nloc;
;         if (old + 1u == (gen + 1u) * nloc) {
;             __builtin_amdgcn_fence(__ATOMIC_RELEASE, "agent");
;             asm volatile("s_waitcnt vmcnt(0)" ::: "memory");
;             const unsigned og = xb_add(&bar[XB_TOP], 1u);
;             const unsigned tg = og / nx;
;             if (og + 1u == (tg + 1u) * nx) xb_add(&bar[XB_TOPGEN], 1u);
;             else XB_SPIN(xb_ld(&bar[XB_TOPGEN]) == tg, bar);
.Lfl1:
	v_mov_b32_e32 v3, 0x23030
	ds_read_b32 v3, v3
	s_waitcnt lgkmcnt(0)
	v_readfirstlane_b32 s100, v3
	s_nop 0
	s_cmp_eq_u32 s100, 0
	s_cbranch_scc0 .Lfl1d
	s_sleep 1
	s_branch .Lfl1
.Lfl1d:
	s_cmp_eq_u32 s100, 2
	s_cbranch_scc1 .Lloc_1
	v_mbcnt_lo_u32_b32 v1, s16, 0
	v_mbcnt_hi_u32_b32 v1, s17, v1
	v_cmp_eq_u32_e32 vcc, 0, v1
	s_and_saveexec_b64 s[18:19], vcc
	s_cbranch_execz .LBB0_143
	s_bcnt1_i32_b64 s3, s[16:17]
	v_readlane_b32 s4, v240, 16
	v_mov_b32_e32 v2, 0
	v_mov_b32_e32 v3, s3
	v_readlane_b32 s5, v240, 17
	s_nop 4
	global_atomic_add v2, v2, v3, s[4:5] sc0

; __device__ __forceinline__ unsigned xb_ld(unsigned* p)              { return __hip_atomic_load(p, __ATOMIC_RELAXED, __HIP_MEMORY_SCOPE_AGENT); }
; __device__ __forceinline__ unsigned xb_add(unsigned* p, unsigned v) { return __hip_atomic_fetch_add(p, v, __ATOMIC_RELAXED, __HIP_MEMORY_SCOPE_AGENT); }
; #define XB_SPIN(cond, bar) do { unsigned _sp = 0; while (cond) { __builtin_amdgcn_s_sleep(1); \
;     if ((++_sp & 255u) == 0u) { if (xb_ld(&(bar)[XB_TMO])) break; if (_sp > XB_SPIN_CAP) { atomicAdd(&(bar)[XB_TMO], 1u); break; } } } } while (0)
; __device__ __forceinline__ void xcd_barrier(const XcdBarrier& b) {
;     ...
;     if (threadIdx.x == 0) {
;         unsigned* bar = b.bar;
;         __builtin_amdgcn_s_waitcnt(0);
;         unsigned nloc = b.st[0], nx = b.st[1];
;         if (nloc == 0u) { xcd_barrier_complete(bar, b.x, nloc, nx); b.st[0] = nloc; b.st[1] = nx; }
;         const unsigned old = xb_add(&bar[XB_XSUB(b.x)], 1u);
;         const unsigned gen = old / nloc;
;         if (old + 1u == (gen + 1u) * nloc) {
;             __builtin_amdgcn_fence(__ATOMIC_RELEASE, "agent");
;             asm volatile("s_waitcnt vmcnt(0)" ::: "memory");
;             const unsigned og = xb_add(&bar[XB_TOP], 1u);
;             const unsigned tg = og / nx;
;             if (og + 1u == (tg + 1u) * nx) xb_add(&bar[XB_TOPGEN], 1u);
;             else XB_SPIN(xb_ld(&bar[XB_TOPGEN]) == tg, bar);
;             __builtin_amdgcn_fence(__ATOMIC_ACQUIRE, "agent");
;             xb_add(&bar[XB_XGEN(b.x)], 1u);
;             asm volatile("s_waitcnt vmcnt(0)" ::: "memory");
.Lloc_1:
	s_mov_b64 s[16:17], exec
	v_mbcnt_lo_u32_b32 v0, s16, 0
	v_mbcnt_hi_u32_b32 v0, s17, v0
	v_cmp_eq_u32_e32 vcc, 0, v0
	s_waitcnt vmcnt(0)
	s_and_saveexec_b64 s[18:19], vcc
	s_cbranch_execz .LBB0_159
	s_bcnt1_i32_b64 s3, s[16:17]
	v_readlane_b32 s4, v240, 14
	v_mov_b32_e32 v0, 0
	v_mov_b32_e32 v1, s3
	v_readlane_b32 s5, v240, 15
	s_nop 4
	global_atomic_add v0, v1, s[4:5]

; __device__ __forceinline__ int opaque_tid() { int t = threadIdx.x; asm volatile("" : "+v"(t)); return t; }
; #define LAS __attribute__((address_space(3)))
; __device__ __forceinline__ void transpose_item(const float* W, int K, int N, bf16* WT, const float* gain, LAS float* scr, int item, int nblk, int lane) {
;     const int kb = item / nblk, nb = item % nblk, k0 = 64 * kb, n0 = 64 * nb;
;     const int kr = lane >> 4, nc = 4 * (lane & 15);
;     const bool ok = (n0 + nc) < N;
; __device__ __forceinline__ void p0b_mlp_weights(const Args& a, LAS unsigned char* lds) {
;     const int tid = opaque_tid(), lane = tid & 63, wave = tid >> 6;
;     LAS float* scr = (LAS float*)(lds + wave * 16640);
;     const int gw = blockIdx.x * NWAVES + wave, NGW = gridDim.x * NWAVES;
;     constexpr int I_UP = (D_ / 64) * (FF / 64), I_DN = (FF / 64) * (D_ / 64);
;     for (int it = gw; it < I_UP + I_DN; it += NGW) {
;         if (it < I_UP) transpose_item(a.w_up, D_, FF, (bf16*)(a.ws + WS_WUP), a.ln_mlp_g, scr, it, FF / 64, lane);
;         else transpose_item(a.w_dn, FF, D_, (bf16*)(a.ws + WS_WDN), nullptr, scr, it - I_UP, D_ / 64, lane);
.LBB0_160:
	s_or_b64 exec, exec, s[0:1]
	s_cmpk_lt_i32 s2, 0x200
	v_mov_b32_e32 v12, v210
	s_cselect_b64 s[16:17], -1, 0
	s_waitcnt lgkmcnt(0)
	s_barrier
	v_writelane_b32 v130, s0, 0
	v_writelane_b32 v130, s10, 1
	v_writelane_b32 v130, s11, 2
	v_writelane_b32 v130, s20, 3
	v_writelane_b32 v130, s21, 4
	v_writelane_b32 v130, s22, 5
	v_writelane_b32 v130, s23, 6
	v_writelane_b32 v130, s24, 7
	v_writelane_b32 v130, s25, 8
	v_writelane_b32 v130, s26, 9
	v_writelane_b32 v130, s42, 10
	v_writelane_b32 v130, s43, 11
	v_writelane_b32 v130, s44, 12
	v_writelane_b32 v130, s45, 13
	v_writelane_b32 v130, s50, 14
	v_writelane_b32 v130, s51, 15
	v_writelane_b32 v130, s64, 16
	v_writelane_b32 v130, s65, 17
	v_writelane_b32 v130, s66, 18
	v_writelane_b32 v130, s67, 19
	v_writelane_b32 v130, s68, 20
	v_writelane_b32 v130, s69, 21
	v_writelane_b32 v130, s70, 22
	v_writelane_b32 v130, s71, 23
	v_writelane_b32 v130, s72, 24
	v_writelane_b32 v130, s73, 25
	v_writelane_b32 v130, s74, 26
	v_writelane_b32 v130, s75, 27
	v_writelane_b32 v130, s76, 28
	v_writelane_b32 v130, s77, 29
	v_writelane_b32 v130, s78, 30
	v_writelane_b32 v130, s79, 31
	v_writelane_b32 v130, s33, 32
	v_writelane_b32 v130, s40, 33
	s_lshl_b32 s40, s94, 2
	s_lshl_b32 s33, s94, 8
	s_add_u32 s10, s92, 0xf6a0000
	v_mov_b32_e32 v0, v210
	s_addc_u32 s11, s93, 0
	v_readlane_b32 s0, v241, 19
	v_ashrrev_i32_e32 v1, 6, v0
	s_add_u32 s50, s92, 0xeea0000
	v_add_u32_e32 v84, s0, v1
	v_add_u32_e32 v84, 0x400, v84
	s_mul_i32 s100, s94, 4
	v_subrev_u32_e32 v84, s100, v84
	v_subrev_u32_e32 v2, 0x400, v84
	s_movk_i32 s20, 0x400
	s_addc_u32 s51, s93, 0
	v_cmp_gt_u32_e32 vcc, s20, v2
	s_and_saveexec_b64 s[20:21], vcc
	v_readlane_b32 s64, v241, 2
	v_readlane_b32 s72, v241, 10
	v_readlane_b32 s73, v241, 11
	v_readlane_b32 s74, v241, 12
	v_readlane_b32 s75, v241, 13
	v_readlane_b32 s76, v241, 14
	v_readlane_b32 s77, v241, 15
	v_readlane_b32 s78, v241, 16
	v_readlane_b32 s79, v241, 17
	v_readlane_b32 s65, v241, 3
	v_readlane_b32 s66, v241, 4
	v_readlane_b32 s67, v241, 5
	v_readlane_b32 s68, v241, 6
	v_readlane_b32 s69, v241, 7
	v_readlane_b32 s70, v241, 8
	v_readlane_b32 s71, v241, 9
	s_cbranch_execz .Lw1_554
	s_movk_i32 s24, 0x4100
	v_mul_lo_u32 v2, v1, s24
	v_add_u32_e32 v3, 0, v2
	v_bfe_u32 v85, v0, 4, 2
	v_lshlrev_b32_e32 v2, 2, v0
	v_bfe_u32 v87, v0, 3, 3
	v_lshlrev_b32_e32 v0, 3, v0
	v_and_b32_e32 v6, 56, v0
	v_and_b32_e32 v86, 60, v2
	v_mul_u32_u24_e32 v0, 0x104, v6
	v_lshlrev_b32_e32 v7, 2, v87
	v_lshlrev_b32_e32 v2, 2, v86
	v_add3_u32 v88, v3, v0, v7
	v_mov_b32_e32 v0, 0
	v_readlane_b32 s0, v241, 18
	v_add_u32_e32 v4, v3, v2
	v_mul_u32_u24_e32 v5, 0x104, v85
	v_mov_b32_e32 v3, v0
	v_lshl_add_u32 v96, v1, 6, s0
	v_add_u32_e32 v96, 0x10000, v96
	s_lshl_b32 s101, s94, 8
	v_subrev_u32_e32 v96, s101, v96
	v_lshlrev_b32_e32 v1, 2, v1
	s_cmp_lg_u64 s[72:73], 0
	v_lshl_add_u64 v[68:69], s[76:77], 0, v[2:3]
	v_lshl_add_u64 v[70:71], s[74:75], 0, v[2:3]
	v_lshlrev_b32_e32 v2, 1, v6
	v_lshl_add_u32 v1, s2, 5, v1
	v_add_u32_e32 v98, v4, v5
	s_mov_b64 s[22:23], 0
	s_cselect_b64 s[42:43], -1, 0
	v_or_b32_e32 v89, 8, v87
	v_or_b32_e32 v90, 16, v87
	v_or_b32_e32 v91, 24, v87
	v_or_b32_e32 v92, 32, v87
	v_or_b32_e32 v93, 40, v87
	v_or_b32_e32 v94, 48, v87
	v_or_b32_e32 v95, 56, v87
	v_lshl_add_u64 v[72:73], s[10:11], 0, v[2:3]
	v_lshl_add_u64 v[74:75], s[50:51], 0, v[2:3]
	v_add_u32_e32 v97, 0x40000, v1
	s_lshl_b32 s101, s94, 4
	v_subrev_u32_e32 v97, s101, v97
	s_lshl_b32 s26, s94, 4
	v_add_u32_e32 v99, 0x410, v98
	v_add_u32_e32 v100, 0x418, v98
	v_add_u32_e32 v101, 0x820, v98
	v_add_u32_e32 v102, 0x828, v98
	v_add_u32_e32 v103, 0xc30, v98
	v_add_u32_e32 v104, 0xc38, v98
	v_add_u32_e32 v105, 0x1040, v98
	v_add_u32_e32 v106, 0x1048, v98
	v_add_u32_e32 v107, 0x1450, v98
	v_add_u32_e32 v108, 0x1458, v98
	v_add_u32_e32 v109, 0x1860, v98
	v_add_u32_e32 v110, 0x1868, v98
	v_add_u32_e32 v111, 0x1c70, v98
	v_add_u32_e32 v112, 0x1c78, v98
	v_add_u32_e32 v113, 0x2080, v98
	v_add_u32_e32 v114, 0x2088, v98
	v_add_u32_e32 v115, 0x2490, v98
	v_add_u32_e32 v116, 0x2498, v98
	v_add_u32_e32 v117, 0x28a0, v98
	v_add_u32_e32 v118, 0x28a8, v98
	v_add_u32_e32 v119, 0x2cb0, v98
	v_add_u32_e32 v120, 0x2cb8, v98
	v_add_u32_e32 v121, 0x30c0, v98
	v_add_u32_e32 v122, 0x30c8, v98
	v_add_u32_e32 v123, 0x34d0, v98
	s_branch .Lw1_517

; __device__ __forceinline__ unsigned xb_ld(unsigned* p)              { return __hip_atomic_load(p, __ATOMIC_RELAXED, __HIP_MEMORY_SCOPE_AGENT); }
; __device__ __forceinline__ unsigned xb_add(unsigned* p, unsigned v) { return __hip_atomic_fetch_add(p, v, __ATOMIC_RELAXED, __HIP_MEMORY_SCOPE_AGENT); }
; #define XB_SPIN(cond, bar) do { unsigned _sp = 0; while (cond) { __builtin_amdgcn_s_sleep(1); \
;     if ((++_sp & 255u) == 0u) { if (xb_ld(&(bar)[XB_TMO])) break; if (_sp > XB_SPIN_CAP) { atomicAdd(&(bar)[XB_TMO], 1u); break; } } } } while (0)
; __device__ __forceinline__ void xcd_barrier(const XcdBarrier& b) {
;     asm volatile("s_waitcnt vmcnt(0)" ::: "memory");
;     __syncthreads();
;     if (threadIdx.x == 0) {
;         unsigned* bar = b.bar;
;         __builtin_amdgcn_s_waitcnt(0);
;         unsigned nloc = b.st[0], nx = b.st[1];
;         if (nloc == 0u) { xcd_barrier_complete(bar, b.x, nloc, nx); b.st[0] = nloc; b.st[1] = nx; }
;         const unsigned old = xb_add(&bar[XB_XSUB(b.x)], 1u);
;         const unsigned gen = old / nloc;
;         if (old + 1u == (gen + 1u) * nloc) {
;             __builtin_amdgcn_fence(__ATOMIC_RELEASE, "agent");
;             asm volatile("s_waitcnt vmcnt(0)" ::: "memory");
;             const unsigned og = xb_add(&bar[XB_TOP], 1u);
;             const unsigned tg = og / nx;
;             if (og + 1u == (tg + 1u) * nx) xb_add(&bar[XB_TOPGEN], 1u);
;             else XB_SPIN(xb_ld(&bar[XB_TOPGEN]) == tg, bar);
.LBB0_430:
	s_andn2_saveexec_b64 s[24:25], s[24:25]
	s_cbranch_execz .LBB0_450
	s_mov_b64 s[24:25], exec
	buffer_wbl2 sc1
	s_waitcnt lgkmcnt(0)
	s_waitcnt vmcnt(0)
	v_mov_b32_e32 v3, 0x23030
	ds_read_b32 v3, v3
	s_waitcnt lgkmcnt(0)
	v_readfirstlane_b32 s100, v3
	s_nop 0
	s_cmp_eq_u32 s100, 2
	s_cbranch_scc1 .Lloc_3
	v_mbcnt_lo_u32_b32 v1, s24, 0
	v_mbcnt_hi_u32_b32 v1, s25, v1
	v_cmp_eq_u32_e32 vcc, 0, v1
	s_and_saveexec_b64 s[38:39], vcc
	s_cbranch_execz .LBB0_433
	s_bcnt1_i32_b64 s24, s[24:25]
	v_readlane_b32 s0, v240, 16
	v_mov_b32_e32 v2, 0
	v_mov_b32_e32 v3, s24
	v_readlane_b32 s1, v240, 17
	s_nop 4
	global_atomic_add v2, v2, v3, s[0:1] sc0

; __device__ __forceinline__ unsigned xb_ld(unsigned* p)              { return __hip_atomic_load(p, __ATOMIC_RELAXED, __HIP_MEMORY_SCOPE_AGENT); }
; __device__ __forceinline__ unsigned xb_add(unsigned* p, unsigned v) { return __hip_atomic_fetch_add(p, v, __ATOMIC_RELAXED, __HIP_MEMORY_SCOPE_AGENT); }
; #define XB_SPIN(cond, bar) do { unsigned _sp = 0; while (cond) { __builtin_amdgcn_s_sleep(1); \
;     if ((++_sp & 255u) == 0u) { if (xb_ld(&(bar)[XB_TMO])) break; if (_sp > XB_SPIN_CAP) { atomicAdd(&(bar)[XB_TMO], 1u); break; } } } } while (0)
; __device__ __forceinline__ void xcd_barrier(const XcdBarrier& b) {
;     asm volatile("s_waitcnt vmcnt(0)" ::: "memory");
;     __syncthreads();
;     if (threadIdx.x == 0) {
;         unsigned* bar = b.bar;
;         __builtin_amdgcn_s_waitcnt(0);
;         unsigned nloc = b.st[0], nx = b.st[1];
;         if (nloc == 0u) { xcd_barrier_complete(bar, b.x, nloc, nx); b.st[0] = nloc; b.st[1] = nx; }
;         const unsigned old = xb_add(&bar[XB_XSUB(b.x)], 1u);
;         const unsigned gen = old / nloc;
;         if (old + 1u == (gen + 1u) * nloc) {
;             __builtin_amdgcn_fence(__ATOMIC_RELEASE, "agent");
;             asm volatile("s_waitcnt vmcnt(0)" ::: "memory");
;             const unsigned og = xb_add(&bar[XB_TOP], 1u);
;             const unsigned tg = og / nx;
;             if (og + 1u == (tg + 1u) * nx) xb_add(&bar[XB_TOPGEN], 1u);
;             else XB_SPIN(xb_ld(&bar[XB_TOPGEN]) == tg, bar);
.LBB0_491:
	s_andn2_saveexec_b64 s[20:21], s[20:21]
	s_cbranch_execz .LBB0_511
	s_mov_b64 s[20:21], exec
	buffer_wbl2 sc1
	s_waitcnt lgkmcnt(0)
	s_waitcnt vmcnt(0)
	v_mov_b32_e32 v3, 0x23030
	ds_read_b32 v3, v3
	s_waitcnt lgkmcnt(0)
	v_readfirstlane_b32 s100, v3
	s_nop 0
	s_cmp_eq_u32 s100, 2
	s_cbranch_scc1 .Lloc_4
	v_mbcnt_lo_u32_b32 v1, s20, 0
	v_mbcnt_hi_u32_b32 v1, s21, v1
	v_cmp_eq_u32_e32 vcc, 0, v1
	s_and_saveexec_b64 s[22:23], vcc
	s_cbranch_execz .LBB0_494
	s_bcnt1_i32_b64 s20, s[20:21]
	v_readlane_b32 s0, v240, 16
	v_mov_b32_e32 v2, 0
	v_mov_b32_e32 v3, s20
	v_readlane_b32 s1, v240, 17
	s_nop 4
	global_atomic_add v2, v2, v3, s[0:1] sc0

; __device__ __forceinline__ unsigned xb_ld(unsigned* p)              { return __hip_atomic_load(p, __ATOMIC_RELAXED, __HIP_MEMORY_SCOPE_AGENT); }
; __device__ __forceinline__ unsigned xb_add(unsigned* p, unsigned v) { return __hip_atomic_fetch_add(p, v, __ATOMIC_RELAXED, __HIP_MEMORY_SCOPE_AGENT); }
; #define XB_SPIN(cond, bar) do { unsigned _sp = 0; while (cond) { __builtin_amdgcn_s_sleep(1); \
;     if ((++_sp & 255u) == 0u) { if (xb_ld(&(bar)[XB_TMO])) break; if (_sp > XB_SPIN_CAP) { atomicAdd(&(bar)[XB_TMO], 1u); break; } } } } while (0)
; __device__ __forceinline__ void xcd_barrier(const XcdBarrier& b) {
;     asm volatile("s_waitcnt vmcnt(0)" ::: "memory");
;     __syncthreads();
;     if (threadIdx.x == 0) {
;         unsigned* bar = b.bar;
;         __builtin_amdgcn_s_waitcnt(0);
;         unsigned nloc = b.st[0], nx = b.st[1];
;         if (nloc == 0u) { xcd_barrier_complete(bar, b.x, nloc, nx); b.st[0] = nloc; b.st[1] = nx; }
;         const unsigned old = xb_add(&bar[XB_XSUB(b.x)], 1u);
;         const unsigned gen = old / nloc;
;         if (old + 1u == (gen + 1u) * nloc) {
;             __builtin_amdgcn_fence(__ATOMIC_RELEASE, "agent");
;             asm volatile("s_waitcnt vmcnt(0)" ::: "memory");
;             const unsigned og = xb_add(&bar[XB_TOP], 1u);
;             const unsigned tg = og / nx;
;             if (og + 1u == (tg + 1u) * nx) xb_add(&bar[XB_TOPGEN], 1u);
;             else XB_SPIN(xb_ld(&bar[XB_TOPGEN]) == tg, bar);
.LBB0_684:
	s_andn2_saveexec_b64 s[18:19], s[18:19]
	s_cbranch_execz .LBB0_704
	s_mov_b64 s[18:19], exec
	buffer_wbl2 sc1
	s_waitcnt lgkmcnt(0)
	s_waitcnt vmcnt(0)
	v_mov_b32_e32 v3, 0x23030
	ds_read_b32 v3, v3
	s_waitcnt lgkmcnt(0)
	v_readfirstlane_b32 s100, v3
	s_nop 0
	s_cmp_eq_u32 s100, 2
	s_cbranch_scc1 .Lloc_5
	v_mbcnt_lo_u32_b32 v1, s18, 0
	v_mbcnt_hi_u32_b32 v1, s19, v1
	v_cmp_eq_u32_e32 vcc, 0, v1
	s_and_saveexec_b64 s[20:21], vcc
	s_cbranch_execz .LBB0_687
	s_bcnt1_i32_b64 s18, s[18:19]
	v_readlane_b32 s4, v240, 16
	v_mov_b32_e32 v2, 0
	v_mov_b32_e32 v3, s18
	v_readlane_b32 s5, v240, 17
	s_nop 4
	global_atomic_add v2, v2, v3, s[4:5] sc0

; __device__ __forceinline__ unsigned xb_ld(unsigned* p)              { return __hip_atomic_load(p, __ATOMIC_RELAXED, __HIP_MEMORY_SCOPE_AGENT); }
; __device__ __forceinline__ unsigned xb_add(unsigned* p, unsigned v) { return __hip_atomic_fetch_add(p, v, __ATOMIC_RELAXED, __HIP_MEMORY_SCOPE_AGENT); }
; #define XB_SPIN(cond, bar) do { unsigned _sp = 0; while (cond) { __builtin_amdgcn_s_sleep(1); \
;     if ((++_sp & 255u) == 0u) { if (xb_ld(&(bar)[XB_TMO])) break; if (_sp > XB_SPIN_CAP) { atomicAdd(&(bar)[XB_TMO], 1u); break; } } } } while (0)
; __device__ __forceinline__ void xcd_barrier(const XcdBarrier& b) {
;     asm volatile("s_waitcnt vmcnt(0)" ::: "memory");
;     __syncthreads();
;     if (threadIdx.x == 0) {
;         unsigned* bar = b.bar;
;         __builtin_amdgcn_s_waitcnt(0);
;         unsigned nloc = b.st[0], nx = b.st[1];
;         if (nloc == 0u) { xcd_barrier_complete(bar, b.x, nloc, nx); b.st[0] = nloc; b.st[1] = nx; }
;         const unsigned old = xb_add(&bar[XB_XSUB(b.x)], 1u);
;         const unsigned gen = old / nloc;
;         if (old + 1u == (gen + 1u) * nloc) {
;             __builtin_amdgcn_fence(__ATOMIC_RELEASE, "agent");
;             asm volatile("s_waitcnt vmcnt(0)" ::: "memory");
;             const unsigned og = xb_add(&bar[XB_TOP], 1u);
;             const unsigned tg = og / nx;
;             if (og + 1u == (tg + 1u) * nx) xb_add(&bar[XB_TOPGEN], 1u);
;             else XB_SPIN(xb_ld(&bar[XB_TOPGEN]) == tg, bar);
.LBB0_797:
	s_andn2_saveexec_b64 s[8:9], s[8:9]
	s_cbranch_execz .LBB0_817
	s_mov_b64 s[8:9], exec
	buffer_wbl2 sc1
	s_waitcnt lgkmcnt(0)
	s_waitcnt vmcnt(0)
	v_mov_b32_e32 v3, 0x23030
	ds_read_b32 v3, v3
	s_waitcnt lgkmcnt(0)
	v_readfirstlane_b32 s100, v3
	s_nop 0
	s_cmp_eq_u32 s100, 2
	s_cbranch_scc1 .Lloc_6
	v_mbcnt_lo_u32_b32 v1, s8, 0
	v_mbcnt_hi_u32_b32 v1, s9, v1
	v_cmp_eq_u32_e32 vcc, 0, v1
	s_and_saveexec_b64 s[16:17], vcc
	s_cbranch_execz .LBB0_800
	s_bcnt1_i32_b64 s8, s[8:9]
	v_readlane_b32 s4, v240, 16
	v_mov_b32_e32 v2, 0
	v_mov_b32_e32 v3, s8
	v_readlane_b32 s5, v240, 17
	s_nop 4
	global_atomic_add v2, v2, v3, s[4:5] sc0

; __device__ __forceinline__ unsigned xb_ld(unsigned* p)              { return __hip_atomic_load(p, __ATOMIC_RELAXED, __HIP_MEMORY_SCOPE_AGENT); }
; __device__ __forceinline__ unsigned xb_add(unsigned* p, unsigned v) { return __hip_atomic_fetch_add(p, v, __ATOMIC_RELAXED, __HIP_MEMORY_SCOPE_AGENT); }
; #define XB_SPIN(cond, bar) do { unsigned _sp = 0; while (cond) { __builtin_amdgcn_s_sleep(1); \
;     if ((++_sp & 255u) == 0u) { if (xb_ld(&(bar)[XB_TMO])) break; if (_sp > XB_SPIN_CAP) { atomicAdd(&(bar)[XB_TMO], 1u); break; } } } } while (0)
; __device__ __forceinline__ void xcd_barrier(const XcdBarrier& b) {
;     asm volatile("s_waitcnt vmcnt(0)" ::: "memory");
;     __syncthreads();
;     if (threadIdx.x == 0) {
;         unsigned* bar = b.bar;
;         __builtin_amdgcn_s_waitcnt(0);
;         unsigned nloc = b.st[0], nx = b.st[1];
;         if (nloc == 0u) { xcd_barrier_complete(bar, b.x, nloc, nx); b.st[0] = nloc; b.st[1] = nx; }
;         const unsigned old = xb_add(&bar[XB_XSUB(b.x)], 1u);
;         const unsigned gen = old / nloc;
;         if (old + 1u == (gen + 1u) * nloc) {
;             __builtin_amdgcn_fence(__ATOMIC_RELEASE, "agent");
;             asm volatile("s_waitcnt vmcnt(0)" ::: "memory");
;             const unsigned og = xb_add(&bar[XB_TOP], 1u);
;             const unsigned tg = og / nx;
;             if (og + 1u == (tg + 1u) * nx) xb_add(&bar[XB_TOPGEN], 1u);
;             else XB_SPIN(xb_ld(&bar[XB_TOPGEN]) == tg, bar);
.LBB0_876:
	s_andn2_saveexec_b64 s[4:5], s[4:5]
	s_cbranch_execz .LBB0_896
	s_mov_b64 s[4:5], exec
	buffer_wbl2 sc1
	s_waitcnt lgkmcnt(0)
	s_waitcnt vmcnt(0)
	v_mov_b32_e32 v3, 0x23030
	ds_read_b32 v3, v3
	s_waitcnt lgkmcnt(0)
	v_readfirstlane_b32 s100, v3
	s_nop 0
	s_cmp_eq_u32 s100, 2
	s_cbranch_scc1 .Lloc_7
	v_mbcnt_lo_u32_b32 v1, s4, 0
	v_mbcnt_hi_u32_b32 v1, s5, v1
	v_cmp_eq_u32_e32 vcc, 0, v1
	s_and_saveexec_b64 s[6:7], vcc
	s_cbranch_execz .LBB0_879
	s_bcnt1_i32_b64 s4, s[4:5]
	v_mov_b32_e32 v3, s4
	v_readlane_b32 s4, v240, 16
	v_mov_b32_e32 v2, 0
	v_readlane_b32 s5, v240, 17
	s_nop 4
	global_atomic_add v2, v2, v3, s[4:5] sc0
